# GEMM phase prologues: k-tile 1 DMA loads issued with k-tile 0 (before the first wait/barrier) instead of one memory round trip later
# speedup vs baseline: 1.0069x; 1.0069x over previous
.LBB0_309:
	s_mul_i32 s3, s74, 0x8400
	v_readlane_b32 s48, v252, 45
	s_ashr_i32 s4, s3, 31
	v_readlane_b32 s60, v252, 57
	v_readlane_b32 s61, v252, 58
	s_add_u32 s30, s60, s3
	s_addc_u32 s31, s61, s4
	s_mov_b64 s[4:5], 0x80
	v_readlane_b32 s50, v252, 47
	s_lshl_b32 s1, s1, 5
	v_lshl_add_u64 v[8:9], v[8:9], 0, s[4:5]
	s_add_i32 m0, s15, 0x18000
	v_readlane_b32 s51, v252, 48
	s_and_b32 s44, s1, 0x60
	global_load_lds_dwordx4 v[8:9], off
	v_lshl_add_u64 v[6:7], v[6:7], 0, s[4:5]
	s_add_i32 m0, s15, 0x1a000
	s_add_i32 s50, s15, 0x8000
	s_lshl_b32 s41, s0, 6
	s_lshl_b32 s3, s0, 13
	s_lshl_b32 s1, s44, 7
	global_load_lds_dwordx4 v[6:7], off
	v_lshl_add_u64 v[2:3], v[2:3], 0, s[4:5]
	s_mov_b32 m0, s50
	s_add_i32 s51, s15, 0xa000
	global_load_lds_dwordx4 v[2:3], off
	v_lshl_add_u64 v[2:3], v[4:5], 0, s[4:5]
	s_add_u32 s4, s26, 0x40080
	s_mov_b32 m0, s51
	s_addc_u32 s5, s27, 0
	global_load_lds_dwordx4 v[2:3], off
	v_lshl_add_u64 v[2:3], s[4:5], 0, v[170:171]
	s_add_i32 m0, s15, 0x1c000
	v_bfe_u32 v189, v10, 4, 2
	global_load_lds_dwordx4 v[2:3], off
	v_lshl_add_u64 v[2:3], s[4:5], 0, v[172:173]
	s_add_i32 m0, s15, 0x1e000
	v_and_b32_e32 v188, 15, v10
	global_load_lds_dwordx4 v[2:3], off
	s_waitcnt vmcnt(8)
	s_barrier
	v_lshlrev_b32_e32 v13, 4, v189
	v_lshlrev_b32_e32 v10, 2, v10
	v_lshl_or_b32 v13, v188, 6, v13
	v_and_b32_e32 v10, 32, v10
	s_cmpk_lt_u32 s2, 0x100
	v_bitop3_b32 v190, v13, s1, v10 bitop3:0xde
	s_cselect_b64 s[36:37], -1, 0
	s_lshl_b32 s1, s0, 10
	s_cmp_gt_i32 s0, 0
	s_cselect_b64 s[38:39], -1, 0
	s_cmp_gt_i32 s0, -2
	s_mul_i32 s0, s74, 0x2600000
	s_cselect_b64 s[46:47], -1, 0
	s_ashr_i32 s2, s0, 31
	s_add_u32 s0, s82, s0
	v_readlane_b32 s62, v252, 59
	s_addc_u32 s2, s83, s2
	v_readlane_b32 s63, v252, 60
	s_add_u32 s62, s0, 0x1680000
	v_bitop3_b32 v14, v13, s3, v10 bitop3:0xde
	s_addc_u32 s63, s2, 0
	v_readlane_b32 s2, v253, 25
	s_mov_b32 s4, s2
	s_mul_hi_i32 s0, s2, 0x180000
	s_mul_i32 s2, s2, 0x180000
	v_readlane_b32 s3, v253, 26
	s_add_u32 s2, s82, s2
	s_addc_u32 s0, s83, s0
	s_mul_hi_i32 s3, s4, 0xffea0000
	s_mul_i32 s4, s4, 0xffea0000
	s_add_u32 s2, s2, s4
	s_addc_u32 s0, s0, s3
	s_add_u32 s64, s2, 0x15000000
	s_addc_u32 s65, s0, 0
	v_lshlrev_b32_e32 v2, 14, v0
	v_readlane_b32 s49, v252, 46
	s_add_u32 s48, s82, 0x1f000000
	v_and_b32_e32 v2, 0xffff8000, v2
	s_addc_u32 s49, s83, 0
	v_and_b32_e32 v0, 1, v0
	v_lshl_add_u32 v2, v11, 11, v2
	s_waitcnt vmcnt(6)
	s_add_u32 s10, s82, 0x1f160000
	v_lshl_or_b32 v0, v0, 6, v2
	s_addc_u32 s11, s83, 0
	s_add_i32 s67, s1, 0
	v_lshl_add_u32 v178, v12, 1, v0
	v_readlane_b32 s52, v252, 49
	v_readlane_b32 s53, v252, 50
	v_readlane_b32 s54, v252, 51
	s_mov_b32 s69, 0
	s_add_i32 s66, s67, 0x21c00
	s_add_i32 s67, s67, 0x21800
	v_add_u32_e32 v180, 0x20000, v178
	v_mov_b32_e32 v181, v1
	v_mov_b32_e32 v179, v1
	v_add_u32_e32 v191, 0, v14
	v_readlane_b32 s55, v252, 52
	v_readlane_b32 s56, v252, 53
	v_readlane_b32 s57, v252, 54
	v_readlane_b32 s58, v252, 55
	v_readlane_b32 s59, v252, 56
	s_barrier
	s_branch .LBB0_314

.LBB0_345:
	s_and_b32 s28, s4, 3
	s_mov_b64 s[4:5], 0x80
	v_lshl_add_u64 v[8:9], v[8:9], 0, s[4:5]
	s_add_i32 m0, s11, 0x18000
	global_load_lds_dwordx4 v[8:9], off
	v_lshl_add_u64 v[6:7], v[6:7], 0, s[4:5]
	s_add_i32 m0, s11, 0x1a000
	s_add_i32 s41, s11, 0x8000
	s_lshl_b32 s19, s0, 6
	s_lshl_b32 s26, s0, 13
	s_lshl_b32 s40, s28, 5
	s_lshl_b32 s27, s28, 12
	global_load_lds_dwordx4 v[6:7], off
	v_lshl_add_u64 v[2:3], v[2:3], 0, s[4:5]
	s_mov_b32 m0, s41
	s_add_i32 s44, s11, 0xa000
	global_load_lds_dwordx4 v[2:3], off
	v_lshl_add_u64 v[2:3], v[4:5], 0, s[4:5]
	s_add_u32 s4, s8, 0x40080
	s_mov_b32 m0, s44
	s_addc_u32 s5, s9, 0
	global_load_lds_dwordx4 v[2:3], off
	v_lshl_add_u64 v[2:3], s[4:5], 0, v[196:197]
	s_add_i32 m0, s11, 0x1c000
	v_bfe_u32 v246, v12, 4, 2
	global_load_lds_dwordx4 v[2:3], off
	v_lshl_add_u64 v[2:3], s[4:5], 0, v[198:199]
	s_add_i32 m0, s11, 0x1e000
	v_and_b32_e32 v245, 15, v12
	global_load_lds_dwordx4 v[2:3], off
	s_waitcnt vmcnt(8)
	s_barrier
	v_lshlrev_b32_e32 v2, 4, v246
	v_lshlrev_b32_e32 v3, 2, v12
	v_lshl_or_b32 v2, v245, 6, v2
	v_and_b32_e32 v3, 32, v3
	s_cmpk_lt_u32 s1, 0x100
	v_bitop3_b32 v4, v2, s26, v3 bitop3:0xde
	v_bitop3_b32 v247, v2, s27, v3 bitop3:0xde
	s_cselect_b64 s[26:27], -1, 0
	s_lshl_b32 s0, s0, 2
	s_or_b32 s0, s0, s28
	s_ashr_i32 s1, s0, 31
	s_lshl_b64 s[0:1], s[0:1], 10
	s_add_u32 s0, s82, s0
	s_addc_u32 s1, s83, s1
	s_add_u32 s50, s0, 0xf000000
	s_addc_u32 s51, s1, 0
	v_readlane_b32 s0, v253, 25
	s_add_u32 s3, s82, s3
	v_readlane_b32 s1, v253, 26
	s_addc_u32 s2, s83, s2
	s_lshl_b64 s[0:1], s[0:1], 19
	s_sub_u32 s0, 0, s0
	s_subb_u32 s1, 0, s1
	v_lshlrev_b32_e32 v2, 14, v0
	s_add_u32 s0, s3, s0
	v_and_b32_e32 v2, 0xffff8000, v2
	s_addc_u32 s1, s2, s1
	v_and_b32_e32 v0, 1, v0
	v_lshl_add_u32 v2, v10, 11, v2
	s_add_u32 s28, s0, 0x15080000
	v_lshl_or_b32 v0, v0, 6, v2
	s_addc_u32 s29, s1, 0
	v_lshl_add_u32 v2, v11, 1, v0
	s_mov_b64 s[0:1], 0x40080
	v_mov_b32_e32 v3, v1
	s_waitcnt vmcnt(6)
	v_add_u32_e32 v0, 0x20000, v2
	v_lshl_add_u64 v[206:207], v[2:3], 0, s[0:1]
	v_mov_b32_e32 v2, v1
	v_lshl_add_u64 v[204:205], v[0:1], 0, s[0:1]
	v_mov_b32_e32 v0, v1
	v_add_u32_e32 v248, 0, v4
	v_mov_b64_e32 v[6:7], v[2:3]
	v_mov_b64_e32 v[10:11], v[2:3]
	v_mov_b64_e32 v[14:15], v[2:3]
	v_mov_b64_e32 v[18:19], v[2:3]
	v_mov_b64_e32 v[22:23], v[2:3]
	v_mov_b64_e32 v[26:27], v[2:3]
	v_mov_b64_e32 v[30:31], v[2:3]
	v_mov_b64_e32 v[34:35], v[2:3]
	v_mov_b64_e32 v[38:39], v[2:3]
	v_mov_b64_e32 v[42:43], v[2:3]
	v_mov_b64_e32 v[46:47], v[2:3]
	v_mov_b64_e32 v[50:51], v[2:3]
	v_mov_b64_e32 v[54:55], v[2:3]
	v_mov_b64_e32 v[58:59], v[2:3]
	v_mov_b64_e32 v[62:63], v[2:3]
	v_mov_b64_e32 v[66:67], v[2:3]
	v_mov_b64_e32 v[70:71], v[2:3]
	v_mov_b64_e32 v[74:75], v[2:3]
	v_mov_b64_e32 v[78:79], v[2:3]
	v_mov_b64_e32 v[82:83], v[2:3]
	v_mov_b64_e32 v[86:87], v[2:3]
	v_mov_b64_e32 v[90:91], v[2:3]
	v_mov_b64_e32 v[94:95], v[2:3]
	v_mov_b64_e32 v[98:99], v[2:3]
	v_mov_b64_e32 v[102:103], v[2:3]
	v_mov_b64_e32 v[106:107], v[2:3]
	v_mov_b64_e32 v[110:111], v[2:3]
	v_mov_b64_e32 v[114:115], v[2:3]
	v_mov_b64_e32 v[118:119], v[2:3]
	v_mov_b64_e32 v[122:123], v[2:3]
	v_mov_b64_e32 v[126:127], v[2:3]
	v_mov_b64_e32 v[130:131], v[2:3]
	s_mov_b32 s53, 6
	s_mov_b32 s54, 0
	v_mov_b64_e32 v[4:5], v[0:1]
	v_mov_b64_e32 v[8:9], v[0:1]
	v_mov_b64_e32 v[12:13], v[0:1]
	v_mov_b64_e32 v[16:17], v[0:1]
	v_mov_b64_e32 v[20:21], v[0:1]
	v_mov_b64_e32 v[24:25], v[0:1]
	v_mov_b64_e32 v[28:29], v[0:1]
	v_mov_b64_e32 v[32:33], v[0:1]
	v_mov_b64_e32 v[36:37], v[0:1]
	v_mov_b64_e32 v[40:41], v[0:1]
	v_mov_b64_e32 v[44:45], v[0:1]
	v_mov_b64_e32 v[48:49], v[0:1]
	v_mov_b64_e32 v[52:53], v[0:1]
	v_mov_b64_e32 v[56:57], v[0:1]
	v_mov_b64_e32 v[60:61], v[0:1]
	v_mov_b64_e32 v[64:65], v[0:1]
	v_mov_b64_e32 v[68:69], v[0:1]
	v_mov_b64_e32 v[72:73], v[0:1]
	v_mov_b64_e32 v[76:77], v[0:1]
	v_mov_b64_e32 v[80:81], v[0:1]
	v_mov_b64_e32 v[84:85], v[0:1]
	v_mov_b64_e32 v[88:89], v[0:1]
	v_mov_b64_e32 v[92:93], v[0:1]
	v_mov_b64_e32 v[96:97], v[0:1]
	v_mov_b64_e32 v[100:101], v[0:1]
	v_mov_b64_e32 v[104:105], v[0:1]
	v_mov_b64_e32 v[108:109], v[0:1]
	v_mov_b64_e32 v[112:113], v[0:1]
	v_mov_b64_e32 v[116:117], v[0:1]
	v_mov_b64_e32 v[120:121], v[0:1]
	v_mov_b64_e32 v[124:125], v[0:1]
	v_mov_b64_e32 v[128:129], v[0:1]
	s_mov_b64 s[36:37], s[8:9]
	s_mov_b64 s[34:35], s[6:7]
	s_mov_b64 s[62:63], 0x100
	s_barrier
	s_branch .LBB0_347

.LBB0_514:
	s_add_u32 s34, s82, 0x1b000000
	s_addc_u32 s35, s83, 0
	s_ashr_i32 s19, s18, 31
	s_lshl_b64 s[2:3], s[18:19], 19
	s_add_u32 s5, s82, s2
	s_addc_u32 s6, s83, s3
	s_add_u32 s36, s5, 0x1f510000
	s_addc_u32 s37, s6, 0
	s_lshl_b32 s2, s18, 7
	s_ashr_i32 s3, s2, 31
	s_lshl_b64 s[2:3], s[2:3], 2
	s_add_u32 s2, s82, s2
	s_addc_u32 s3, s83, s3
	v_bfe_u32 v211, v14, 4, 2
	s_add_u32 s49, s2, 0x4000
	v_and_b32_e32 v210, 15, v14
	v_lshlrev_b32_e32 v0, 4, v211
	v_lshlrev_b32_e32 v14, 2, v14
	s_addc_u32 s60, s3, 0
	s_and_b32 s2, s1, 3
	s_lshl_b32 s61, s0, 6
	v_lshl_or_b32 v0, v210, 6, v0
	s_lshl_b32 s0, s0, 13
	v_and_b32_e32 v14, 32, v14
	v_bitop3_b32 v19, v0, s0, v14 bitop3:0xde
	s_lshl_b32 s0, s2, 12
	v_bitop3_b32 v212, v0, s0, v14 bitop3:0xde
	s_mov_b64 s[0:1], 0x80
	v_lshl_add_u64 v[2:3], v[2:3], 0, s[0:1]
	s_add_i32 m0, s53, 0x18000
	global_load_lds_dwordx4 v[2:3], off
	v_lshl_add_u64 v[2:3], v[6:7], 0, s[0:1]
	s_add_i32 m0, s53, 0x1a000
	s_add_i32 s59, s53, 0x8000
	global_load_lds_dwordx4 v[2:3], off
	v_lshl_add_u64 v[2:3], v[10:11], 0, s[0:1]
	s_mov_b32 m0, s59
	s_add_i32 s56, s53, 0xa000
	global_load_lds_dwordx4 v[2:3], off
	v_lshl_add_u64 v[2:3], v[12:13], 0, s[0:1]
	s_mov_b32 m0, s56
	s_lshl_b32 s58, s2, 5
	global_load_lds_dwordx4 v[2:3], off
	v_lshl_add_u64 v[2:3], v[4:5], 0, s[0:1]
	s_add_i32 m0, s53, 0x1c000
	v_readlane_b32 s11, v254, 1
	global_load_lds_dwordx4 v[2:3], off
	v_lshl_add_u64 v[2:3], v[8:9], 0, s[0:1]
	s_add_i32 m0, s53, 0x1e000
	s_cmpk_lt_u32 s4, 0x100
	global_load_lds_dwordx4 v[2:3], off
	s_waitcnt vmcnt(8)
	s_barrier
	s_cselect_b64 s[18:19], -1, 0
	s_and_b32 s0, s4, 0xffffff00
	s_lshl_b32 s1, s2, 6
	s_or_b32 s57, s1, s0
	s_mul_i32 s0, s11, 0x2600000
	s_ashr_i32 s1, s0, 31
	s_add_u32 s3, s82, s0
	s_addc_u32 s4, s83, s1
	s_add_u32 s0, s3, 0x1680000
	v_writelane_b32 v253, s0, 55
	s_addc_u32 s0, s4, 0
	v_writelane_b32 v253, s0, 57
	v_and_b32_e32 v0, 1, v15
	v_readlane_b32 s0, v253, 25
	s_mul_i32 s8, s0, 0x180000
	s_mul_hi_i32 s7, s0, 0x180000
	s_add_u32 s9, s82, s8
	s_addc_u32 s10, s83, s7
	v_readlane_b32 s1, v253, 26
	s_add_u32 s0, s9, 0x15140000
	s_addc_u32 s1, s10, 0
	v_writelane_b32 v253, s0, 47
	v_lshlrev_b32_e32 v2, 1, v18
	s_waitcnt vmcnt(6)
	v_lshl_add_u32 v186, v0, 6, v2
	v_writelane_b32 v253, s1, 48
	v_mov_b32_e32 v2, v1
	v_readlane_b32 s0, v253, 22
	v_readlane_b32 s1, v253, 23
	s_mov_b32 s38, s0
	s_ashr_i32 s39, s0, 31
	s_lshl_b64 s[0:1], s[38:39], 18
	s_add_u32 s0, s3, s0
	s_addc_u32 s1, s4, s1
	s_add_u32 s0, s0, 0x1580000
	s_addc_u32 s1, s1, 0
	v_writelane_b32 v253, s0, 49
	s_cmp_lt_i32 s38, 2
	v_mov_b32_e32 v3, v1
	v_writelane_b32 v253, s1, 50
	s_cselect_b64 s[0:1], -1, 0
	v_writelane_b32 v255, s0, 27
	v_add3_u32 v213, v17, v16, 64
	v_mov_b32_e32 v0, v1
	v_writelane_b32 v255, s1, 28
	s_lshl_b64 s[0:1], s[38:39], 19
	s_add_u32 s0, s3, s0
	s_addc_u32 s1, s4, s1
	s_add_u32 s30, s0, 0x1280000
	s_addc_u32 s31, s1, 0
	v_writelane_b32 v254, s30, 7
	v_add_u32_e32 v214, 0, v19
	v_mov_b64_e32 v[6:7], v[2:3]
	v_writelane_b32 v254, s31, 8
	s_add_u32 s30, s9, 0x15080000
	s_addc_u32 s31, s10, 0
	v_writelane_b32 v253, s30, 51
	v_mov_b64_e32 v[10:11], v[2:3]
	v_mov_b64_e32 v[14:15], v[2:3]
	v_writelane_b32 v253, s31, 52
	s_add_u32 s30, s0, 0x1080000
	s_addc_u32 s31, s1, 0
	s_add_u32 s9, s82, 0x15000000
	s_addc_u32 s10, s83, 0
	s_add_u32 s8, s9, s8
	v_writelane_b32 v253, s30, 53
	v_writelane_b32 v255, s9, 31
	s_addc_u32 s9, s10, s7
	v_writelane_b32 v253, s31, 54
	s_add_u32 s0, s0, 0xe80000
	v_writelane_b32 v253, s0, 43
	s_addc_u32 s0, s1, 0
	v_writelane_b32 v255, s10, 41
	v_writelane_b32 v253, s0, 45
	s_or_b32 s0, s75, s11
	v_writelane_b32 v255, s8, 33
	s_cmp_eq_u32 s0, 0
	s_movk_i32 s0, 0x6c0
	v_writelane_b32 v255, s9, 34
	s_cselect_b32 s8, 0x700, s0
	v_readlane_b32 s0, v252, 39
	v_readlane_b32 s1, v252, 40
	s_mov_b32 s9, s1
	v_writelane_b32 v255, s8, 57
	s_lshr_b32 s0, s8, 3
	s_mov_b32 s65, s1
	v_writelane_b32 v255, s9, 58
	v_writelane_b32 v255, s0, 63
	s_add_u32 s0, s3, 0x100000
	v_writelane_b32 v253, s0, 59
	s_addc_u32 s0, s4, 0
	s_mul_i32 s1, s38, 0x160000
	v_writelane_b32 v253, s0, 61
	s_mul_hi_i32 s0, s38, 0x160000
	s_mov_b32 s8, s38
	s_add_u32 s1, s3, s1
	v_writelane_b32 v253, s8, 22
	s_addc_u32 s0, s4, s0
	v_mov_b64_e32 v[18:19], v[2:3]
	v_writelane_b32 v253, s9, 23
	s_add_u32 s8, s1, 0x2180000
	s_addc_u32 s9, s0, 0
	s_lshl_b32 s0, s2, 2
	v_writelane_b32 v255, s8, 59
	s_add_i32 s44, s0, 0
	s_add_i32 s44, s44, 0x21c00
	v_writelane_b32 v255, s9, 60
	s_add_u32 s62, s5, 0x1f550000
	v_readlane_b32 s0, v255, 39
	s_addc_u32 s63, s6, 0
	s_lshl_b32 s64, s75, 24
	v_readlane_b32 s1, v255, 40
	s_cmp_lg_u64 s[0:1], 0
	v_mov_b64_e32 v[22:23], v[2:3]
	v_mov_b64_e32 v[26:27], v[2:3]
	v_mov_b64_e32 v[30:31], v[2:3]
	v_mov_b64_e32 v[34:35], v[2:3]
	v_mov_b64_e32 v[38:39], v[2:3]
	v_mov_b64_e32 v[42:43], v[2:3]
	v_mov_b64_e32 v[46:47], v[2:3]
	v_mov_b64_e32 v[50:51], v[2:3]
	v_mov_b64_e32 v[54:55], v[2:3]
	v_mov_b64_e32 v[58:59], v[2:3]
	v_mov_b64_e32 v[62:63], v[2:3]
	v_mov_b64_e32 v[66:67], v[2:3]
	v_mov_b64_e32 v[70:71], v[2:3]
	v_mov_b64_e32 v[74:75], v[2:3]
	v_mov_b64_e32 v[78:79], v[2:3]
	v_mov_b64_e32 v[82:83], v[2:3]
	v_mov_b64_e32 v[86:87], v[2:3]
	v_mov_b64_e32 v[90:91], v[2:3]
	v_mov_b64_e32 v[94:95], v[2:3]
	v_mov_b64_e32 v[98:99], v[2:3]
	v_mov_b64_e32 v[102:103], v[2:3]
	v_mov_b64_e32 v[106:107], v[2:3]
	v_mov_b64_e32 v[110:111], v[2:3]
	v_mov_b64_e32 v[114:115], v[2:3]
	v_mov_b64_e32 v[118:119], v[2:3]
	v_mov_b64_e32 v[122:123], v[2:3]
	v_mov_b64_e32 v[126:127], v[2:3]
	v_mov_b64_e32 v[130:131], v[2:3]
	s_mov_b32 s30, 0
	v_writelane_b32 v254, s75, 3
	s_cselect_b64 s[66:67], -1, 0
	v_mov_b64_e32 v[4:5], v[0:1]
	v_mov_b64_e32 v[8:9], v[0:1]
	v_mov_b64_e32 v[12:13], v[0:1]
	v_mov_b64_e32 v[16:17], v[0:1]
	v_mov_b64_e32 v[20:21], v[0:1]
	v_mov_b64_e32 v[24:25], v[0:1]
	v_mov_b64_e32 v[28:29], v[0:1]
	v_mov_b64_e32 v[32:33], v[0:1]
	v_mov_b64_e32 v[36:37], v[0:1]
	v_mov_b64_e32 v[40:41], v[0:1]
	v_mov_b64_e32 v[44:45], v[0:1]
	v_mov_b64_e32 v[48:49], v[0:1]
	v_mov_b64_e32 v[52:53], v[0:1]
	v_mov_b64_e32 v[56:57], v[0:1]
	v_mov_b64_e32 v[60:61], v[0:1]
	v_mov_b64_e32 v[64:65], v[0:1]
	v_mov_b64_e32 v[68:69], v[0:1]
	v_mov_b64_e32 v[72:73], v[0:1]
	v_mov_b64_e32 v[76:77], v[0:1]
	v_mov_b64_e32 v[80:81], v[0:1]
	v_mov_b64_e32 v[84:85], v[0:1]
	v_mov_b64_e32 v[88:89], v[0:1]
	v_mov_b64_e32 v[92:93], v[0:1]
	v_mov_b64_e32 v[96:97], v[0:1]
	v_mov_b64_e32 v[100:101], v[0:1]
	v_mov_b64_e32 v[104:105], v[0:1]
	v_mov_b64_e32 v[108:109], v[0:1]
	v_mov_b64_e32 v[112:113], v[0:1]
	v_mov_b64_e32 v[116:117], v[0:1]
	v_mov_b64_e32 v[120:121], v[0:1]
	v_mov_b64_e32 v[124:125], v[0:1]
	v_mov_b64_e32 v[128:129], v[0:1]
	s_barrier
	s_branch .LBB0_517

.LBB0_854:
	v_bfe_u32 v139, v14, 4, 2
	s_lshl_b32 s10, s10, 5
	v_and_b32_e32 v138, 15, v14
	v_lshlrev_b32_e32 v0, 4, v139
	v_lshlrev_b32_e32 v14, 2, v14
	s_and_b32 s81, s10, 0x60
	s_lshl_b32 s80, s11, 6
	v_lshl_or_b32 v0, v138, 6, v0
	s_lshl_b32 s11, s11, 13
	v_and_b32_e32 v14, 32, v14
	s_lshl_b32 s10, s81, 7
	v_bitop3_b32 v19, v0, s11, v14 bitop3:0xde
	v_bitop3_b32 v140, v0, s10, v14 bitop3:0xde
	s_mov_b64 s[10:11], 0x80
	v_lshl_add_u64 v[2:3], v[2:3], 0, s[10:11]
	s_add_i32 m0, s76, 0x18000
	global_load_lds_dwordx4 v[2:3], off
	v_lshl_add_u64 v[2:3], v[6:7], 0, s[10:11]
	s_add_i32 m0, s76, 0x1a000
	s_add_i32 s82, s76, 0x8000
	global_load_lds_dwordx4 v[2:3], off
	v_lshl_add_u64 v[2:3], v[10:11], 0, s[10:11]
	s_mov_b32 m0, s82
	s_add_i32 s83, s76, 0xa000
	global_load_lds_dwordx4 v[2:3], off
	v_lshl_add_u64 v[2:3], v[12:13], 0, s[10:11]
	s_mov_b32 m0, s83
	v_readlane_b32 s46, v253, 29
	global_load_lds_dwordx4 v[2:3], off
	v_lshl_add_u64 v[2:3], v[4:5], 0, s[10:11]
	s_add_i32 m0, s76, 0x1c000
	v_readlane_b32 s47, v253, 30
	v_lshl_add_u64 v[2:3], v[8:9], 0, s[10:11]
	s_add_i32 m0, s76, 0x1e000
	s_cmpk_lt_u32 s14, 0x100
	s_waitcnt vmcnt(6)
	s_barrier
	s_mul_i32 s10, s19, 0x2600000
	s_cselect_b64 s[12:13], -1, 0
	s_ashr_i32 s11, s10, 31
	s_add_u32 s14, s46, s10
	s_addc_u32 s15, s47, s11
	s_add_u32 s10, s14, 0x1680000
	v_readlane_b32 s36, v253, 25
	v_writelane_b32 v255, s10, 41
	s_addc_u32 s10, s15, 0
	s_mul_i32 s26, s36, 0x180000
	s_mul_hi_i32 s27, s36, 0x180000
	s_add_u32 s34, s46, s26
	s_addc_u32 s35, s47, s27
	v_writelane_b32 v255, s10, 27
	s_add_u32 s10, s34, 0x15140000
	s_addc_u32 s11, s35, 0
	v_writelane_b32 v255, s10, 39
	s_mov_b32 s28, s19
	v_readlane_b32 s37, v253, 26
	v_writelane_b32 v255, s11, 40
	v_readlane_b32 s10, v253, 22
	v_readlane_b32 s11, v253, 23
	s_mov_b32 s30, s10
	s_ashr_i32 s31, s10, 31
	s_lshl_b64 s[10:11], s[30:31], 18
	s_add_u32 s10, s14, s10
	s_addc_u32 s11, s15, s11
	s_add_u32 s10, s10, 0x1580000
	s_addc_u32 s11, s11, 0
	v_writelane_b32 v255, s10, 29
	s_cmp_lt_i32 s30, 4
	s_cselect_b64 s[18:19], -1, 0
	v_writelane_b32 v255, s11, 30
	s_lshl_b64 s[10:11], s[30:31], 19
	s_add_u32 s10, s14, s10
	s_addc_u32 s11, s15, s11
	s_add_u32 s20, s10, 0x1280000
	s_addc_u32 s21, s11, 0
	s_add_u32 s22, s34, 0x15080000
	s_addc_u32 s23, s35, 0
	s_add_u32 s24, s10, 0x1080000
	s_addc_u32 s25, s11, 0
	s_add_u32 s86, s46, 0x15000000
	s_addc_u32 s87, s47, 0
	s_add_u32 s26, s86, s26
	s_addc_u32 s27, s87, s27
	s_add_u32 s10, s10, 0xe80000
	v_writelane_b32 v253, s10, 37
	s_addc_u32 s10, s11, 0
	v_writelane_b32 v254, s28, 1
	v_writelane_b32 v253, s10, 22
	v_readlane_b32 s10, v254, 3
	s_or_b32 s10, s10, s28
	s_cmp_eq_u32 s10, 0
	s_movk_i32 s10, 0x6c0
	s_cselect_b32 s28, 0x700, s10
	v_readlane_b32 s10, v252, 39
	s_lshr_b32 s90, s28, 3
	v_readlane_b32 s11, v252, 40
	s_add_u32 s10, s14, 0x100000
	s_mov_b32 s29, s11
	v_writelane_b32 v255, s10, 33
	s_addc_u32 s10, s15, 0
	s_mul_i32 s11, s30, 0x160000
	v_writelane_b32 v255, s10, 57
	s_mul_hi_i32 s10, s30, 0x160000
	s_add_u32 s11, s14, s11
	s_addc_u32 s10, s15, s10
	s_mov_b32 s72, s30
	s_add_u32 s30, s11, 0x2180000
	s_addc_u32 s31, s10, 0
	s_mul_i32 s11, s36, 0xffea0000
	s_mul_hi_i32 s10, s36, 0xffea0000
	s_add_u32 s14, s26, s11
	s_addc_u32 s15, s27, s10
	s_lshl_b64 s[10:11], s[36:37], 18
	s_sub_u32 s10, 0, s10
	s_subb_u32 s11, 0, s11
	s_add_u32 s10, s34, s10
	s_addc_u32 s11, s35, s11
	s_add_u32 s36, s10, 0x15100000
	s_addc_u32 s37, s11, 0
	s_sub_u32 s2, 0, s2
	s_subb_u32 s3, 0, s3
	s_add_u32 s38, s22, s2
	s_addc_u32 s39, s23, s3
	v_writelane_b32 v255, s14, 59
	s_add_u32 s2, s46, 0xf000000
	s_addc_u32 s3, s47, 0
	v_writelane_b32 v255, s15, 60
	v_writelane_b32 v255, s2, 63
	v_and_b32_e32 v0, 1, v15
	v_lshlrev_b32_e32 v2, 1, v18
	v_writelane_b32 v254, s3, 0
	s_add_u32 s2, s46, 0x7800000
	s_addc_u32 s3, s47, 0
	s_add_u32 s93, s46, 0x5400000
	s_waitcnt vmcnt(4)
	s_addc_u32 s94, s47, 0
	v_lshl_add_u32 v134, v0, 6, v2
	v_mov_b32_e32 v2, v1
	v_mov_b32_e32 v3, v1
	v_writelane_b32 v255, s2, 61
	s_add_u32 s95, s46, 0x5000000
	v_add3_u32 v141, v17, v16, 64
	v_mov_b32_e32 v0, v1
	v_add_u32_e32 v142, 0, v19
	v_mov_b64_e32 v[6:7], v[2:3]
	v_mov_b64_e32 v[10:11], v[2:3]
	v_mov_b64_e32 v[14:15], v[2:3]
	v_mov_b64_e32 v[18:19], v[2:3]
	v_mov_b64_e32 v[22:23], v[2:3]
	v_mov_b64_e32 v[26:27], v[2:3]
	v_mov_b64_e32 v[30:31], v[2:3]
	v_mov_b64_e32 v[34:35], v[2:3]
	v_mov_b64_e32 v[38:39], v[2:3]
	v_mov_b64_e32 v[42:43], v[2:3]
	v_mov_b64_e32 v[46:47], v[2:3]
	v_mov_b64_e32 v[50:51], v[2:3]
	v_mov_b64_e32 v[54:55], v[2:3]
	v_mov_b64_e32 v[58:59], v[2:3]
	v_mov_b64_e32 v[62:63], v[2:3]
	v_mov_b64_e32 v[66:67], v[2:3]
	v_mov_b64_e32 v[70:71], v[2:3]
	v_mov_b64_e32 v[74:75], v[2:3]
	v_mov_b64_e32 v[78:79], v[2:3]
	v_mov_b64_e32 v[82:83], v[2:3]
	v_mov_b64_e32 v[86:87], v[2:3]
	v_mov_b64_e32 v[90:91], v[2:3]
	v_mov_b64_e32 v[94:95], v[2:3]
	v_mov_b64_e32 v[98:99], v[2:3]
	v_mov_b64_e32 v[102:103], v[2:3]
	v_mov_b64_e32 v[106:107], v[2:3]
	v_mov_b64_e32 v[110:111], v[2:3]
	v_mov_b64_e32 v[114:115], v[2:3]
	v_mov_b64_e32 v[118:119], v[2:3]
	v_mov_b64_e32 v[122:123], v[2:3]
	v_mov_b64_e32 v[126:127], v[2:3]
	v_mov_b64_e32 v[130:131], v[2:3]
	s_mov_b32 s84, 0
	v_writelane_b32 v255, s3, 62
	s_addc_u32 s96, s47, 0
	v_mov_b64_e32 v[4:5], v[0:1]
	v_mov_b64_e32 v[8:9], v[0:1]
	v_mov_b64_e32 v[12:13], v[0:1]
	v_mov_b64_e32 v[16:17], v[0:1]
	v_mov_b64_e32 v[20:21], v[0:1]
	v_mov_b64_e32 v[24:25], v[0:1]
	v_mov_b64_e32 v[28:29], v[0:1]
	v_mov_b64_e32 v[32:33], v[0:1]
	v_mov_b64_e32 v[36:37], v[0:1]
	v_mov_b64_e32 v[40:41], v[0:1]
	v_mov_b64_e32 v[44:45], v[0:1]
	v_mov_b64_e32 v[48:49], v[0:1]
	v_mov_b64_e32 v[52:53], v[0:1]
	v_mov_b64_e32 v[56:57], v[0:1]
	v_mov_b64_e32 v[60:61], v[0:1]
	v_mov_b64_e32 v[64:65], v[0:1]
	v_mov_b64_e32 v[68:69], v[0:1]
	v_mov_b64_e32 v[72:73], v[0:1]
	v_mov_b64_e32 v[76:77], v[0:1]
	v_mov_b64_e32 v[80:81], v[0:1]
	v_mov_b64_e32 v[84:85], v[0:1]
	v_mov_b64_e32 v[88:89], v[0:1]
	v_mov_b64_e32 v[92:93], v[0:1]
	v_mov_b64_e32 v[96:97], v[0:1]
	v_mov_b64_e32 v[100:101], v[0:1]
	v_mov_b64_e32 v[104:105], v[0:1]
	v_mov_b64_e32 v[108:109], v[0:1]
	v_mov_b64_e32 v[112:113], v[0:1]
	v_mov_b64_e32 v[116:117], v[0:1]
	v_mov_b64_e32 v[120:121], v[0:1]
	v_mov_b64_e32 v[124:125], v[0:1]
	v_mov_b64_e32 v[128:129], v[0:1]
	s_barrier
	s_branch .LBB0_857

.LBB0_1010:
	s_mov_b64 s[8:9], 0x80
	v_lshl_add_u64 v[2:3], v[2:3], 0, s[8:9]
	s_add_i32 m0, s49, 0x18000
	global_load_lds_dwordx4 v[2:3], off
	v_lshl_add_u64 v[2:3], v[4:5], 0, s[8:9]
	s_add_i32 m0, s49, 0x1a000
	s_add_i32 s56, s49, 0x8000
	global_load_lds_dwordx4 v[2:3], off
	v_lshl_add_u64 v[2:3], v[10:11], 0, s[8:9]
	s_mov_b32 m0, s56
	s_add_i32 s57, s49, 0xa000
	global_load_lds_dwordx4 v[2:3], off
	v_lshl_add_u64 v[2:3], v[12:13], 0, s[8:9]
	s_mov_b32 m0, s57
	v_bfe_u32 v179, v14, 4, 2
	global_load_lds_dwordx4 v[2:3], off
	v_lshl_add_u64 v[2:3], v[6:7], 0, s[8:9]
	s_add_i32 m0, s49, 0x1c000
	v_and_b32_e32 v178, 15, v14
	global_load_lds_dwordx4 v[2:3], off
	v_lshl_add_u64 v[2:3], v[8:9], 0, s[8:9]
	s_add_i32 m0, s49, 0x1e000
	v_lshlrev_b32_e32 v0, 4, v179
	global_load_lds_dwordx4 v[2:3], off
	s_waitcnt vmcnt(8)
	s_barrier
	v_lshlrev_b32_e32 v14, 2, v14
	s_and_b32 s4, s3, 3
	v_lshl_or_b32 v0, v178, 6, v0
	s_lshl_b32 s5, s2, 13
	v_and_b32_e32 v14, 32, v14
	s_lshl_b32 s54, s2, 6
	v_bitop3_b32 v18, v0, s5, v14 bitop3:0xde
	s_lshl_b32 s55, s4, 5
	s_lshl_b32 s5, s4, 12
	s_cmpk_lt_u32 s6, 0x100
	s_cselect_b64 s[18:19], -1, 0
	s_add_u32 s20, s82, 0x4e00000
	v_bitop3_b32 v180, v0, s5, v14 bitop3:0xde
	s_addc_u32 s21, s83, 0
	s_bfe_u32 s5, s6, 0x10006
	s_cmp_eq_u32 s5, 0
	s_cselect_b64 s[22:23], -1, 0
	s_lshl_b32 s2, s2, 2
	s_or_b32 s2, s2, s4
	s_bfe_u32 s58, s3, 0x10001
	s_ashr_i32 s3, s2, 31
	s_lshl_b32 s59, s5, 5
	s_lshl_b32 s60, s75, 14
	s_lshl_b64 s[24:25], s[2:3], 10
	s_add_u32 s26, s82, 0xd800000
	s_mul_i32 s2, s7, 0x2600000
	s_addc_u32 s27, s83, 0
	s_ashr_i32 s3, s2, 31
	s_add_u32 s61, s82, 0x15000000
	s_addc_u32 s62, s83, 0
	s_lshr_b32 s63, s12, 3
	s_add_u32 s2, s82, s2
	s_addc_u32 s3, s83, s3
	s_add_u32 s64, s2, 0x100000
	s_addc_u32 s65, s3, 0
	s_add_u32 s28, s82, 0xf000000
	s_addc_u32 s29, s83, 0
	s_add_u32 s30, s82, 0x7800000
	v_lshlrev_b32_e32 v0, 14, v15
	s_addc_u32 s31, s83, 0
	v_and_b32_e32 v0, 0xffff8000, v0
	s_add_u32 s44, s82, 0x5400000
	v_and_b32_e32 v2, 1, v15
	v_lshl_add_u32 v0, v16, 11, v0
	s_waitcnt vmcnt(6)
	v_readlane_b32 s4, v252, 39
	s_addc_u32 s66, s83, 0
	v_lshl_or_b32 v0, v2, 6, v0
	v_readlane_b32 s5, v252, 40
	s_add_u32 s67, s82, 0x5000000
	v_lshl_add_u32 v144, v17, 1, v0
	s_mov_b32 s40, 0
	s_mov_b32 s13, s5
	s_addc_u32 s68, s83, 0
	v_add_u32_e32 v146, 0x20000, v144
	v_mov_b32_e32 v147, v1
	v_mov_b32_e32 v145, v1
	v_add_u32_e32 v181, 0, v18
	s_mov_b64 s[38:39], s[0:1]
	s_barrier
	s_branch .LBB0_1012
